# gemm_in 128x128 tail tiles (P cols 14336.., only read by gemm_branch) moved from phase 0 to attention workgroups at phase 4 start, hidden behind the serial scan
# speedup vs baseline: 1.1156x; 1.0055x over previous
; #define ZERO_ACC(acc)                                  \
;   _Pragma("unroll") for (int i_ = 0; i_ < 4; ++i_)     \
;   _Pragma("unroll") for (int j_ = 0; j_ < 4; ++j_) acc[i_][j_] = (f32x4){0.f, 0.f, 0.f, 0.f};
; __device__ __forceinline__ void phase_gemm_in(const Params p, int l, char* smem, int vb) {
;     ...
;   {
;     u16* Bs = As + 128 * 64;
;     for (int t = vb; t < 256; t += gridDim.x) {
;       f32x4 acc[4][4];
;       ZERO_ACC(acc);
;       int mt = t & 63, nt = 112 + (t >> 6);
;       int m0 = mt * 128, n0 = nt * 128;
;       gemm_main_blk((const u16*)(ws + OFF_H) + (size_t)mt * 32 * 8192,
;                     (const u16*)(ws + OFF_WIN) + (size_t)l * NINP * D_ + (size_t)nt * 32 * 8192, D_, As, Bs, acc);
.LBB0_149:
	s_lshr_b32 s0, s73, 6
	s_cmp_eq_u32 s0, 4
	s_cbranch_scc1 .LBB0_248
	s_cmp_lt_u32 s73, 64
	s_cbranch_scc1 .Ltail_skip
	s_sub_i32 s24, s73, 64
	s_cmp_lt_u32 s73, 256
	s_cbranch_scc1 .Ltail_go
	s_cmp_lt_u32 s73, 320
	s_cbranch_scc1 .Ltail_skip
	s_cmp_gt_u32 s73, 383
	s_cbranch_scc1 .Ltail_skip
	s_sub_i32 s24, s73, 128
.Ltail_go:
	v_readlane_b32 s0, v244, 43
	s_movk_i32 s36, 0x6000
	s_movk_i32 s37, 0x3000
	s_mul_hi_i32 s25, s0, 0x3a00000
	s_mul_i32 s30, s0, 0x3a00000
	s_add_u32 s2, s96, s30
	s_addc_u32 s3, s97, s25
	s_mov_b32 s20, s24

; __device__ __forceinline__ void gemm_main_blk(const u16* __restrict__ A, const u16* __restrict__ B,
;                                           int K, u16* As, u16* Bs, f32x4 (&acc)[4][4]) {
;     ...
;   G_LOAD(ra0, rb0, 0)
;   G_LOAD(ra1, rb1, 64)
;   for (int k0 = 0; k0 < K; k0 += 128) {
;     G_STAGE(ra0, rb0, k0 + 128)
;     G_STAGE(ra1, rb1, k0 + 192)
;   }
.LBB0_520:
	s_add_i32 s22, s1, 0x100
	s_min_u32 s22, s22, 0x7c0
	s_lshl_b32 s70, s22, 8
	s_waitcnt lgkmcnt(0)
	s_barrier
	s_waitcnt vmcnt(15)
	ds_write_b128 v132, v[4:7]
	s_waitcnt vmcnt(14)
	ds_write_b128 v132, v[0:3] offset:16384
	s_waitcnt vmcnt(13)
	ds_write_b128 v132, v[16:19] offset:4096
	s_waitcnt vmcnt(11)
	ds_write_b128 v132, v[20:23] offset:20480
	ds_write_b128 v132, v[12:15] offset:8192
	s_waitcnt vmcnt(10)
	ds_write_b128 v132, v[8:11] offset:24576
	s_waitcnt vmcnt(9)
	ds_write_b128 v132, v[24:27] offset:12288
	s_waitcnt vmcnt(7)
	ds_write_b128 v132, v[36:39] offset:28672
	v_lshl_add_u64 v[8:9], v[128:129], 0, s[70:71]
	v_add_co_u32_e32 v12, vcc, s23, v8
	v_lshl_add_u64 v[10:11], v[130:131], 0, s[70:71]
	s_nop 0
	v_addc_co_u32_e32 v13, vcc, 0, v9, vcc
	v_add_co_u32_e32 v24, vcc, s23, v10
	s_waitcnt lgkmcnt(0)
	s_barrier
	global_load_dwordx4 v[4:7], v[8:9], off
	global_load_dwordx4 v[0:3], v[10:11], off
	v_addc_co_u32_e32 v25, vcc, 0, v11, vcc
	v_add_co_u32_e32 v26, vcc, s37, v8
	v_add_u32_e32 v137, v134, v133
	s_nop 0
	v_addc_co_u32_e32 v27, vcc, 0, v9, vcc
	v_add_co_u32_e32 v36, vcc, s37, v10
	v_add_u32_e32 v166, v134, v135
	s_nop 0
	v_addc_co_u32_e32 v37, vcc, 0, v11, vcc
	global_load_dwordx4 v[16:19], v[12:13], off offset:-4096
	s_nop 0
	global_load_dwordx4 v[12:15], v[12:13], off
	s_nop 0
	global_load_dwordx4 v[20:23], v[24:25], off offset:-4096
	global_load_dwordx4 v[8:11], v[24:25], off
	s_nop 0
	global_load_dwordx4 v[24:27], v[26:27], off
	s_nop 0
	global_load_dwordx4 v[36:39], v[36:37], off
	v_add_u32_e32 v167, v136, v133
	v_add_u32_e32 v168, v136, v135
	ds_read_b128 v[138:141], v137
	ds_read_b128 v[142:145], v137 offset:2048
	ds_read_b128 v[146:149], v166 offset:16384
	ds_read_b128 v[150:153], v166 offset:18432
	ds_read_b128 v[154:157], v137 offset:4096
	ds_read_b128 v[158:161], v137 offset:6144
	ds_read_b128 v[162:165], v166 offset:20480
	ds_read_b128 v[172:175], v166 offset:22528
	ds_read_b128 v[176:179], v167
	ds_read_b128 v[180:183], v167 offset:2048
	ds_read_b128 v[184:187], v168 offset:16384
	ds_read_b128 v[188:191], v168 offset:18432
	ds_read_b128 v[214:217], v167 offset:4096
	ds_read_b128 v[218:221], v167 offset:6144
	ds_read_b128 v[222:225], v168 offset:20480
	ds_read_b128 v[226:229], v168 offset:22528
	s_addk_i32 s1, 0x80
	s_min_u32 s22, s1, 0x700
	s_lshl_b32 s22, s22, 8
	s_add_i32 s70, s22, 0xc000
	s_waitcnt lgkmcnt(0)
	s_barrier
	ds_write_b128 v132, v[32:35]
	s_waitcnt vmcnt(14)
	ds_write_b128 v132, v[28:31] offset:16384
	s_waitcnt vmcnt(13)
	ds_write_b128 v132, v[40:43] offset:4096
	s_waitcnt vmcnt(11)
	ds_write_b128 v132, v[52:55] offset:20480
	ds_write_b128 v132, v[44:47] offset:8192
	s_waitcnt vmcnt(10)
	ds_write_b128 v132, v[48:51] offset:24576
	s_waitcnt vmcnt(9)
	ds_write_b128 v132, v[56:59] offset:12288
	s_waitcnt vmcnt(8)
	ds_write_b128 v132, v[60:63] offset:28672
	v_lshl_add_u64 v[56:57], v[128:129], 0, s[70:71]
	v_add_co_u32_e32 v44, vcc, s23, v56
	v_lshl_add_u64 v[60:61], v[130:131], 0, s[70:71]
	s_nop 0
	v_addc_co_u32_e32 v45, vcc, 0, v57, vcc
	v_add_co_u32_e32 v48, vcc, s23, v60
	s_waitcnt lgkmcnt(0)
	s_barrier
	global_load_dwordx4 v[32:35], v[56:57], off
	global_load_dwordx4 v[28:31], v[60:61], off
	v_addc_co_u32_e32 v49, vcc, 0, v61, vcc
	v_add_co_u32_e32 v56, vcc, s37, v56
	global_load_dwordx4 v[40:43], v[44:45], off offset:-4096
	s_nop 0
	v_addc_co_u32_e32 v57, vcc, 0, v57, vcc
	v_add_co_u32_e32 v60, vcc, s37, v60
	global_load_dwordx4 v[52:55], v[48:49], off offset:-4096
	s_nop 0
	global_load_dwordx4 v[44:47], v[44:45], off
	s_nop 0
	global_load_dwordx4 v[48:51], v[48:49], off
	v_addc_co_u32_e32 v61, vcc, 0, v61, vcc
	global_load_dwordx4 v[56:59], v[56:57], off
	s_waitcnt lgkmcnt(14)
	v_mfma_f32_16x16x32_bf16 v[124:127], v[138:141], v[146:149], v[124:127]
	global_load_dwordx4 v[60:63], v[60:61], off
	v_mfma_f32_16x16x32_bf16 v[120:123], v[138:141], v[150:153], v[120:123]
	v_mfma_f32_16x16x32_bf16 v[116:119], v[138:141], v[162:165], v[116:119]
	v_mfma_f32_16x16x32_bf16 v[112:115], v[138:141], v[172:175], v[112:115]
	v_mfma_f32_16x16x32_bf16 v[108:111], v[142:145], v[146:149], v[108:111]
	v_mfma_f32_16x16x32_bf16 v[104:107], v[142:145], v[150:153], v[104:107]
	v_mfma_f32_16x16x32_bf16 v[100:103], v[142:145], v[162:165], v[100:103]
	v_mfma_f32_16x16x32_bf16 v[96:99], v[142:145], v[172:175], v[96:99]
	v_mfma_f32_16x16x32_bf16 v[138:141], v[154:157], v[146:149], v[92:95]
	v_mfma_f32_16x16x32_bf16 v[142:145], v[154:157], v[150:153], v[88:91]
	v_mfma_f32_16x16x32_bf16 v[230:233], v[154:157], v[162:165], v[80:83]
	v_mfma_f32_16x16x32_bf16 v[154:157], v[154:157], v[172:175], v[76:79]
	v_mfma_f32_16x16x32_bf16 v[146:149], v[158:161], v[146:149], v[72:75]
	v_mfma_f32_16x16x32_bf16 v[150:153], v[158:161], v[150:153], v[68:71]
	v_mfma_f32_16x16x32_bf16 v[162:165], v[158:161], v[162:165], v[64:67]
	v_mfma_f32_16x16x32_bf16 v[158:161], v[158:161], v[172:175], v[84:87]
	s_waitcnt lgkmcnt(13)
	v_mfma_f32_16x16x32_bf16 v[64:67], v[176:179], v[184:187], v[124:127]
	s_waitcnt lgkmcnt(12)
	v_mfma_f32_16x16x32_bf16 v[68:71], v[176:179], v[188:191], v[120:123]
	s_waitcnt lgkmcnt(9)
	v_mfma_f32_16x16x32_bf16 v[72:75], v[176:179], v[222:225], v[116:119]
	s_waitcnt lgkmcnt(8)
	v_mfma_f32_16x16x32_bf16 v[76:79], v[176:179], v[226:229], v[112:115]
	v_mfma_f32_16x16x32_bf16 v[80:83], v[180:183], v[184:187], v[108:111]
	v_mfma_f32_16x16x32_bf16 v[84:87], v[180:183], v[188:191], v[104:107]
	v_mfma_f32_16x16x32_bf16 v[88:91], v[180:183], v[222:225], v[100:103]
	v_mfma_f32_16x16x32_bf16 v[92:95], v[180:183], v[226:229], v[96:99]
	v_mfma_f32_16x16x32_bf16 v[96:99], v[214:217], v[184:187], v[138:141]
	v_mfma_f32_16x16x32_bf16 v[100:103], v[214:217], v[188:191], v[142:145]
	v_mfma_f32_16x16x32_bf16 v[104:107], v[214:217], v[222:225], v[230:233]
	v_mfma_f32_16x16x32_bf16 v[108:111], v[214:217], v[226:229], v[154:157]
	v_mfma_f32_16x16x32_bf16 v[112:115], v[218:221], v[184:187], v[146:149]
	v_mfma_f32_16x16x32_bf16 v[116:119], v[218:221], v[188:191], v[150:153]
	v_mfma_f32_16x16x32_bf16 v[120:123], v[218:221], v[222:225], v[162:165]
	v_mfma_f32_16x16x32_bf16 v[124:127], v[218:221], v[226:229], v[158:161]
	ds_read_b128 v[138:141], v137
	ds_read_b128 v[142:145], v166 offset:16384
	ds_read_b128 v[146:149], v137 offset:2048
	ds_read_b128 v[150:153], v166 offset:18432
	ds_read_b128 v[154:157], v137 offset:4096
	ds_read_b128 v[158:161], v166 offset:20480
	ds_read_b128 v[162:165], v137 offset:6144
	ds_read_b128 v[172:175], v166 offset:22528
	ds_read_b128 v[176:179], v167
	ds_read_b128 v[180:183], v168 offset:16384
	ds_read_b128 v[184:187], v167 offset:2048
	ds_read_b128 v[188:191], v168 offset:18432
	ds_read_b128 v[214:217], v167 offset:4096
	ds_read_b128 v[218:221], v168 offset:20480
	ds_read_b128 v[222:225], v167 offset:6144
	ds_read_b128 v[226:229], v168 offset:22528
	s_waitcnt lgkmcnt(14)
	v_mfma_f32_16x16x32_bf16 v[64:67], v[138:141], v[142:145], v[64:67]
	s_cmpk_lt_u32 s1, 0x780
	s_waitcnt lgkmcnt(12)
	v_mfma_f32_16x16x32_bf16 v[68:71], v[138:141], v[150:153], v[68:71]
	s_waitcnt lgkmcnt(10)
	v_mfma_f32_16x16x32_bf16 v[72:75], v[138:141], v[158:161], v[72:75]
	s_waitcnt lgkmcnt(8)
	v_mfma_f32_16x16x32_bf16 v[76:79], v[138:141], v[172:175], v[76:79]
	v_mfma_f32_16x16x32_bf16 v[80:83], v[146:149], v[142:145], v[80:83]
	v_mfma_f32_16x16x32_bf16 v[84:87], v[146:149], v[150:153], v[84:87]
	v_mfma_f32_16x16x32_bf16 v[88:91], v[146:149], v[158:161], v[88:91]
	v_mfma_f32_16x16x32_bf16 v[92:95], v[146:149], v[172:175], v[92:95]
	v_mfma_f32_16x16x32_bf16 v[138:141], v[154:157], v[142:145], v[96:99]
	v_mfma_f32_16x16x32_bf16 v[146:149], v[154:157], v[150:153], v[100:103]
	v_mfma_f32_16x16x32_bf16 v[230:233], v[154:157], v[158:161], v[104:107]
	v_mfma_f32_16x16x32_bf16 v[154:157], v[154:157], v[172:175], v[108:111]
	v_mfma_f32_16x16x32_bf16 v[142:145], v[162:165], v[142:145], v[112:115]
	v_mfma_f32_16x16x32_bf16 v[150:153], v[162:165], v[150:153], v[116:119]
	v_mfma_f32_16x16x32_bf16 v[158:161], v[162:165], v[158:161], v[120:123]
	v_mfma_f32_16x16x32_bf16 v[162:165], v[162:165], v[172:175], v[124:127]
	s_waitcnt lgkmcnt(6)
	v_mfma_f32_16x16x32_bf16 v[124:127], v[176:179], v[180:183], v[64:67]
	s_waitcnt lgkmcnt(4)
	v_mfma_f32_16x16x32_bf16 v[120:123], v[176:179], v[188:191], v[68:71]
	s_waitcnt lgkmcnt(2)
	v_mfma_f32_16x16x32_bf16 v[116:119], v[176:179], v[218:221], v[72:75]
	s_waitcnt lgkmcnt(0)
	v_mfma_f32_16x16x32_bf16 v[112:115], v[176:179], v[226:229], v[76:79]
	v_mfma_f32_16x16x32_bf16 v[108:111], v[184:187], v[180:183], v[80:83]
	v_mfma_f32_16x16x32_bf16 v[104:107], v[184:187], v[188:191], v[84:87]
	v_mfma_f32_16x16x32_bf16 v[100:103], v[184:187], v[218:221], v[88:91]
	v_mfma_f32_16x16x32_bf16 v[96:99], v[184:187], v[226:229], v[92:95]
	v_mfma_f32_16x16x32_bf16 v[92:95], v[214:217], v[180:183], v[138:141]
	v_mfma_f32_16x16x32_bf16 v[88:91], v[214:217], v[188:191], v[146:149]
	v_mfma_f32_16x16x32_bf16 v[80:83], v[214:217], v[218:221], v[230:233]
	v_mfma_f32_16x16x32_bf16 v[76:79], v[214:217], v[226:229], v[154:157]
	v_mfma_f32_16x16x32_bf16 v[72:75], v[222:225], v[180:183], v[142:145]
	v_mfma_f32_16x16x32_bf16 v[68:71], v[222:225], v[188:191], v[150:153]
	v_mfma_f32_16x16x32_bf16 v[64:67], v[222:225], v[218:221], v[158:161]
	v_mfma_f32_16x16x32_bf16 v[84:87], v[222:225], v[226:229], v[162:165]
	s_cbranch_scc1 .LBB0_520
; __device__ __forceinline__ u16 f2bf(float f) { return (u16)(pack2(f, 0.f) & 0xffffu); }
; __device__ __forceinline__ void phase_gemm_in(const Params p, int l, char* smem, int vb) {
;     ...
;       u16* dst = (u16*)(ws + OFF_P);
;       EPI_LOOP({
;         _Pragma("unroll") for (int r2 = 0; r2 < 4; ++r2) dst[(size_t)(m0 + mr + r2) * NINP + n0 + nc] = f2bf(acc[i][j][r2]);
;       })
;     }
	s_waitcnt vmcnt(14)
	v_mov_b32_e32 v0, v171
	s_lshl_b32 s1, s21, 7
	s_lshl_b32 s0, s0, 7
	v_and_b32_e32 v2, 15, v0
	v_lshrrev_b32_e32 v0, 2, v0
	v_mov_b32_e32 v1, v171
	v_and_or_b32 v0, v0, 12, s1
	s_ashr_i32 s1, s0, 31
	s_lshl_b64 s[0:1], s[0:1], 1
	v_readlane_b32 s22, v246, 6
	v_ashrrev_i32_e32 v3, 1, v1
	v_and_or_b32 v1, v1, 64, v2
	v_readlane_b32 s23, v246, 7
	s_add_u32 s0, s22, s0
	v_and_b32_e32 v3, 0xffffffc0, v3
	s_addc_u32 s1, s23, s1
	v_lshlrev_b32_e32 v168, 1, v1
	s_waitcnt vmcnt(10)
	v_add_u32_e32 v10, v0, v3
	v_lshl_add_u64 v[0:1], s[0:1], 0, v[168:169]
	v_cvt_pk_bf16_f32 v4, v124, s0
	v_mad_i64_i32 v[2:3], s[0:1], v10, s88, v[0:1]
	global_store_short v[2:3], v4, off
	v_or_b32_e32 v4, 1, v10
	v_cvt_pk_bf16_f32 v6, v125, s0
	v_mad_i64_i32 v[4:5], s[0:1], v4, s88, v[0:1]
	global_store_short v[4:5], v6, off
	v_or_b32_e32 v6, 2, v10
	v_cvt_pk_bf16_f32 v8, v126, s0
	v_mad_i64_i32 v[6:7], s[0:1], v6, s88, v[0:1]
	global_store_short v[6:7], v8, off
	v_or_b32_e32 v8, 3, v10
	v_cvt_pk_bf16_f32 v11, v127, s0
	v_mad_i64_i32 v[8:9], s[0:1], v8, s88, v[0:1]
	global_store_short v[8:9], v11, off
	s_nop 0
	v_cvt_pk_bf16_f32 v11, v120, s0
	global_store_short v[2:3], v11, off offset:32
	v_cvt_pk_bf16_f32 v11, v121, s0
	global_store_short v[4:5], v11, off offset:32
	v_cvt_pk_bf16_f32 v11, v122, s0
	global_store_short v[6:7], v11, off offset:32
	v_cvt_pk_bf16_f32 v11, v123, s0
	global_store_short v[8:9], v11, off offset:32
	v_cvt_pk_bf16_f32 v11, v116, s0
	global_store_short v[2:3], v11, off offset:64
	v_cvt_pk_bf16_f32 v11, v117, s0
	global_store_short v[4:5], v11, off offset:64
	v_cvt_pk_bf16_f32 v11, v118, s0
	global_store_short v[6:7], v11, off offset:64
	v_cvt_pk_bf16_f32 v11, v119, s0
	global_store_short v[8:9], v11, off offset:64
	v_cvt_pk_bf16_f32 v11, v112, s0
	global_store_short v[2:3], v11, off offset:96
	v_cvt_pk_bf16_f32 v2, v113, s0
	global_store_short v[4:5], v2, off offset:96
	v_cvt_pk_bf16_f32 v2, v114, s0
	global_store_short v[6:7], v2, off offset:96
	v_cvt_pk_bf16_f32 v2, v115, s0
	global_store_short v[8:9], v2, off offset:96
	v_or_b32_e32 v2, 16, v10
	v_cvt_pk_bf16_f32 v4, v108, s0
	v_mad_i64_i32 v[2:3], s[0:1], v2, s88, v[0:1]
	global_store_short v[2:3], v4, off
	v_or_b32_e32 v4, 17, v10
	v_cvt_pk_bf16_f32 v6, v109, s0
	v_mad_i64_i32 v[4:5], s[0:1], v4, s88, v[0:1]
	global_store_short v[4:5], v6, off
	v_or_b32_e32 v6, 18, v10
	v_cvt_pk_bf16_f32 v8, v110, s0
	v_mad_i64_i32 v[6:7], s[0:1], v6, s88, v[0:1]
	global_store_short v[6:7], v8, off
	v_or_b32_e32 v8, 19, v10
	v_cvt_pk_bf16_f32 v11, v111, s0
	v_mad_i64_i32 v[8:9], s[0:1], v8, s88, v[0:1]
	global_store_short v[8:9], v11, off
	s_nop 0
	v_cvt_pk_bf16_f32 v11, v104, s0
	global_store_short v[2:3], v11, off offset:32
	v_cvt_pk_bf16_f32 v11, v105, s0
	global_store_short v[4:5], v11, off offset:32
	v_cvt_pk_bf16_f32 v11, v106, s0
	global_store_short v[6:7], v11, off offset:32
	v_cvt_pk_bf16_f32 v11, v107, s0
	global_store_short v[8:9], v11, off offset:32
	v_cvt_pk_bf16_f32 v11, v100, s0
	global_store_short v[2:3], v11, off offset:64
	v_cvt_pk_bf16_f32 v11, v101, s0
	global_store_short v[4:5], v11, off offset:64
	v_cvt_pk_bf16_f32 v11, v102, s0
	global_store_short v[6:7], v11, off offset:64
	v_cvt_pk_bf16_f32 v11, v103, s0
	global_store_short v[8:9], v11, off offset:64
	v_cvt_pk_bf16_f32 v11, v96, s0
	global_store_short v[2:3], v11, off offset:96
	v_cvt_pk_bf16_f32 v2, v97, s0
	global_store_short v[4:5], v2, off offset:96
	v_cvt_pk_bf16_f32 v2, v98, s0
	global_store_short v[6:7], v2, off offset:96
	v_cvt_pk_bf16_f32 v2, v99, s0
	global_store_short v[8:9], v2, off offset:96
	v_or_b32_e32 v2, 32, v10
	v_cvt_pk_bf16_f32 v4, v92, s0
	v_mad_i64_i32 v[2:3], s[0:1], v2, s88, v[0:1]
	global_store_short v[2:3], v4, off
	v_or_b32_e32 v4, 33, v10
	v_cvt_pk_bf16_f32 v6, v93, s0
	v_mad_i64_i32 v[4:5], s[0:1], v4, s88, v[0:1]
	global_store_short v[4:5], v6, off
	v_or_b32_e32 v6, 34, v10
	v_cvt_pk_bf16_f32 v8, v94, s0
	v_mad_i64_i32 v[6:7], s[0:1], v6, s88, v[0:1]
	global_store_short v[6:7], v8, off
	v_or_b32_e32 v8, 35, v10
	v_cvt_pk_bf16_f32 v11, v95, s0
	v_mad_i64_i32 v[8:9], s[0:1], v8, s88, v[0:1]
	global_store_short v[8:9], v11, off
	s_nop 0
	v_cvt_pk_bf16_f32 v11, v88, s0
	global_store_short v[2:3], v11, off offset:32
	v_cvt_pk_bf16_f32 v11, v89, s0
	global_store_short v[4:5], v11, off offset:32
	v_cvt_pk_bf16_f32 v11, v90, s0
	global_store_short v[6:7], v11, off offset:32
	v_cvt_pk_bf16_f32 v11, v91, s0
	global_store_short v[8:9], v11, off offset:32
	v_cvt_pk_bf16_f32 v11, v80, s0
	global_store_short v[2:3], v11, off offset:64
	v_cvt_pk_bf16_f32 v11, v81, s0
	global_store_short v[4:5], v11, off offset:64
	v_cvt_pk_bf16_f32 v11, v82, s0
	global_store_short v[6:7], v11, off offset:64
	v_cvt_pk_bf16_f32 v11, v83, s0
	global_store_short v[8:9], v11, off offset:64
	v_cvt_pk_bf16_f32 v11, v76, s0
	global_store_short v[2:3], v11, off offset:96
	v_cvt_pk_bf16_f32 v2, v77, s0
	global_store_short v[4:5], v2, off offset:96
	v_cvt_pk_bf16_f32 v2, v78, s0
	global_store_short v[6:7], v2, off offset:96
	v_cvt_pk_bf16_f32 v2, v79, s0
	global_store_short v[8:9], v2, off offset:96
	v_or_b32_e32 v2, 48, v10
	v_cvt_pk_bf16_f32 v4, v72, s0
	v_mad_i64_i32 v[2:3], s[0:1], v2, s88, v[0:1]
	global_store_short v[2:3], v4, off
	v_or_b32_e32 v4, 49, v10
	v_cvt_pk_bf16_f32 v6, v73, s0
	v_mad_i64_i32 v[4:5], s[0:1], v4, s88, v[0:1]
	global_store_short v[4:5], v6, off
	v_or_b32_e32 v6, 50, v10
	v_cvt_pk_bf16_f32 v8, v74, s0
	v_mad_i64_i32 v[6:7], s[0:1], v6, s88, v[0:1]
	v_or_b32_e32 v9, 51, v10
	global_store_short v[6:7], v8, off
	v_cvt_pk_bf16_f32 v8, v75, s0
	v_mad_i64_i32 v[0:1], s[0:1], v9, s88, v[0:1]
	global_store_short v[0:1], v8, off
	s_nop 0
	v_cvt_pk_bf16_f32 v8, v68, s0
	global_store_short v[2:3], v8, off offset:32
	v_cvt_pk_bf16_f32 v8, v69, s0
	global_store_short v[4:5], v8, off offset:32
	v_cvt_pk_bf16_f32 v8, v70, s0
	global_store_short v[6:7], v8, off offset:32
	v_cvt_pk_bf16_f32 v8, v71, s0
	global_store_short v[0:1], v8, off offset:32
	v_cvt_pk_bf16_f32 v8, v64, s0
	global_store_short v[2:3], v8, off offset:64
	v_cvt_pk_bf16_f32 v8, v65, s0
	global_store_short v[4:5], v8, off offset:64
	v_cvt_pk_bf16_f32 v8, v66, s0
	global_store_short v[6:7], v8, off offset:64
	v_cvt_pk_bf16_f32 v8, v67, s0
	global_store_short v[0:1], v8, off offset:64
	v_cvt_pk_bf16_f32 v8, v84, s0
	global_store_short v[2:3], v8, off offset:96
	v_cvt_pk_bf16_f32 v2, v85, s0
	global_store_short v[4:5], v2, off offset:96
	v_cvt_pk_bf16_f32 v2, v86, s0
	s_add_i32 s20, s20, s86
	global_store_short v[6:7], v2, off offset:96
	v_cvt_pk_bf16_f32 v2, v87, s0
	s_cmpk_gt_i32 s20, 0xff
	global_store_short v[0:1], v2, off offset:96
	s_cbranch_scc0 .LBB0_519
	s_waitcnt lgkmcnt(0)
	s_barrier

; #define ZERO_ACC(acc)                                  \
;   _Pragma("unroll") for (int i_ = 0; i_ < 4; ++i_)     \
;   _Pragma("unroll") for (int j_ = 0; j_ < 4; ++j_) acc[i_][j_] = (f32x4){0.f, 0.f, 0.f, 0.f};
; __device__ __forceinline__ void phase_gemm_in(const Params p, int l, char* smem, int vb) {
;     ...
;   {
;     u16* Bs = As + 128 * 64;
;     for (int t = vb; t < 256; t += gridDim.x) {
;       f32x4 acc[4][4];
;       ZERO_ACC(acc);
;       int mt = t & 63, nt = 112 + (t >> 6);
;       int m0 = mt * 128, n0 = nt * 128;
.LBB0_517:
	s_movk_i32 s36, 0x6000
	s_movk_i32 s37, 0x3000
